# s15 + lever 5: attention K tiles staged global->LDS directly (global_load_lds_dwordx4, swizzle folded into per-lane global address); K VGPR loads and K ds_writes removed from the loop
# baseline (speedup 1.0000x reference)
; __device__ __forceinline__ int v_st(int k, int c) { const int kk = (k & ~0xC) | ((k & 4) << 1) | ((k & 8) >> 1); return ((kk >> 3) * 4 + (c >> 5)) * 512 + ((kk & 7) * 32 + (c & 31)) * 2; }
; __device__ __forceinline__ int v_rd_base(int lane) { return ((lane & 3) << 3) | (((lane >> 2) & 3) << 6) | (((lane >> 4) & 1) << 5) | (((lane >> 5) & 1) << 8); }
; #define SLOAD(i, k0) do { sr_[i].vs0 = St::ld8(&Vh[(long)((k0) + sr) * LDK + sc]); sr_[i].vs1 = St::ld8(&Vh[(long)((k0) + 32 + sr) * LDK + sc]); \
;     sr_[i].ks0 = St::ld8(&Kh[(long)((k0) + sr) * LDK + sc]); sr_[i].ks1 = St::ld8(&Kh[(long)((k0) + 32 + sr) * LDK + sc]); } while (0)
; __device__ __forceinline__ void attn_dense_body(const bf16* __restrict__ Qb, const bf16* __restrict__ Kh, const bf16* __restrict__ Vh,
;                                                 const unsigned short* __restrict__ Gb, unsigned short* __restrict__ Yb, int seq, char* lds, const int tid) {
;     ...
;   const TQ* Qw = Qb + (long)(wid * QBLK + r32) * LDQ + hi * 8;
; #pragma unroll
;   for (int d0 = 0; d0 < 8; ++d0) qr[d0] = SQ::tobf(SQ::ld8(Qw + d0 * 16));
;   const int sr = tid >> 4, sc = (tid & 15) * 8, vst0 = v_st(sr, sc), vst1 = v_st(32 + sr, sc);
;   const int vb0 = (int)(uintptr_t)V_lds + v_rd_base(lane);
;   struct { typename St::T vs0, vs1, ks0, ks1; } sr_[SDEPTH];
;     ...
;   f32x16 pA0, pA1, pB0, pB1; float mnA, mnB, alA, alB; bf16x8 pa0, pa1, pa2, pa3; const int NT = seq / KVBLK;
;   constexpr int SE = 0, SO = SDEPTH - 1;
;   SLOAD(SE, 0); asm volatile("s_waitcnt vmcnt(0)" ::: "memory"); SWRITE(0, SE); __syncthreads();
;   qkt(pA0, pA1, K_lds, qr, r32, hi); partialSM(pA0, pA1, m_reg, mnA, alA);
.LBB0_601:
	s_ashr_i32 s15, s14, 31
	s_and_b32 s7, s6, 15
	s_lshl_b64 s[8:9], s[14:15], 12
	s_add_u32 s8, s2, s8
	s_addc_u32 s9, s3, s9
	s_lshl_b32 s47, s7, 7
	s_lshl_b32 s7, s7, 8
	s_add_u32 s12, s8, s7
	s_addc_u32 s13, s9, 0
	s_mul_i32 s9, s48, 0x440000
	s_mul_hi_i32 s8, s48, 0x440000
	s_add_u32 s7, s34, s9
	s_addc_u32 s16, s35, s8
	s_lshl_b32 s6, s6, 6
	s_and_b32 s49, s6, 0x300
	v_mov_b32_e32 v74, v184
	s_add_u32 s6, s7, s49
	s_addc_u32 s7, s16, 0
	s_waitcnt vmcnt(0)
	v_ashrrev_i32_e32 v16, 4, v74
	s_add_u32 s9, s36, s9
	v_lshlrev_b32_e32 v22, 3, v74
	v_add_u32_e32 v18, 32, v16
	s_addc_u32 s16, s37, s8
	v_and_b32_e32 v96, 0x78, v22
	v_ashrrev_i32_e32 v17, 31, v16
	v_ashrrev_i32_e32 v19, 31, v18
	s_add_u32 s8, s9, s49
	v_lshlrev_b32_e32 v185, 1, v96
	v_lshlrev_b64 v[48:49], 10, v[16:17]
	v_lshlrev_b64 v[8:9], 10, v[18:19]
	s_addc_u32 s9, s16, 0
	v_or_b32_e32 v50, v48, v185
	v_mov_b32_e32 v51, v49
	v_or_b32_e32 v8, v8, v185
	v_lshl_add_u64 v[0:1], s[8:9], 0, v[50:51]
	v_lshl_add_u64 v[4:5], s[8:9], 0, v[8:9]
	v_lshl_add_u64 v[10:11], s[6:7], 0, v[50:51]
	v_lshl_add_u64 v[12:13], s[6:7], 0, v[8:9]
	global_load_dwordx4 v[0:3], v[0:1], off
	s_nop 0
	global_load_dwordx4 v[4:7], v[4:5], off
	s_nop 0
	global_load_dwordx4 v[8:11], v[10:11], off
	s_nop 0
	global_load_dwordx4 v[12:15], v[12:13], off
	v_ashrrev_i32_e32 v187, 6, v74
	v_and_b32_e32 v188, 31, v74
	v_lshlrev_b32_e32 v178, 5, v187
	v_or_b32_e32 v20, v178, v188
	v_ashrrev_i32_e32 v21, 31, v20
	v_bfe_u32 v186, v74, 5, 1
	v_lshlrev_b64 v[20:21], 12, v[20:21]
	v_lshl_add_u64 v[20:21], s[12:13], 0, v[20:21]
	v_lshlrev_b32_e32 v180, 4, v186
	v_mov_b32_e32 v181, v97
	v_lshl_add_u64 v[20:21], v[20:21], 0, v[180:181]
	global_load_dwordx4 v[126:129], v[20:21], off
	global_load_dwordx4 v[122:125], v[20:21], off offset:32
	global_load_dwordx4 v[134:137], v[20:21], off offset:64
	global_load_dwordx4 v[130:133], v[20:21], off offset:96
	global_load_dwordx4 v[118:121], v[20:21], off offset:128
	global_load_dwordx4 v[114:117], v[20:21], off offset:160
	global_load_dwordx4 v[110:113], v[20:21], off offset:192
	global_load_dwordx4 v[106:109], v[20:21], off offset:224
	v_and_b32_e32 v19, 0xfffff0, v16
	v_lshlrev_b32_e32 v23, 1, v16
	v_lshrrev_b32_e32 v24, 1, v16
	v_and_b32_e32 v25, 3, v16
	v_and_or_b32 v19, v23, 8, v19
	v_and_or_b32 v23, v24, 4, v25
	v_and_b32_e32 v24, 0xfffff0, v18
	v_lshlrev_b32_e32 v25, 1, v18
	v_and_b32_e32 v17, 0x70, v74
	v_bfe_u32 v22, v22, 5, 2
	v_lshlrev_b32_e32 v16, 8, v16
	v_lshlrev_b32_e32 v18, 8, v18
	v_lshrrev_b32_e32 v19, 1, v19
	v_and_or_b32 v24, v25, 8, v24
	v_bitop3_b32 v16, v185, v16, v17 bitop3:0xde
	v_bitop3_b32 v17, v185, v18, v17 bitop3:0xde
	v_or_b32_e32 v18, v19, v22
	v_lshrrev_b32_e32 v19, 1, v24
	v_lshlrev_b32_e32 v23, 6, v23
	v_and_b32_e32 v26, 48, v185
	v_add_u32_e32 v202, 0, v16
	v_add_u32_e32 v203, 0, v17
	v_lshlrev_b32_e32 v16, 9, v18
	v_or_b32_e32 v17, v19, v22
	v_or3_b32 v16, v16, v23, v26
	v_lshlrev_b32_e32 v17, 9, v17
	v_lshlrev_b32_e32 v52, 4, v74
	v_or3_b32 v17, v17, v23, v26
	v_add_u32_e32 v204, 0, v16
	v_add_u32_e32 v205, 0, v17
	s_waitcnt vmcnt(0)
	s_add_i32 s12, 0, 0x10000
	v_and_b32_e32 v208, 63, v74
	s_cmp_lg_u32 0, -1
	s_cselect_b32 s51, 0, 0
	s_mov_b32 s16, s17
	s_mov_b32 s18, s17
	s_mov_b32 s19, s17
	s_mov_b32 s20, s17
	s_mov_b32 s21, s17
	s_mov_b32 s22, s17
	s_waitcnt vmcnt(11)
	ds_write_b128 v204, v[0:3]
	s_waitcnt vmcnt(10)
	ds_write_b128 v205, v[4:7]
	s_waitcnt vmcnt(9)
	ds_write_b128 v202, v[8:11] offset:32768
	s_waitcnt vmcnt(8)
	ds_write_b128 v203, v[12:15] offset:32768
	v_lshlrev_b32_e32 v12, 8, v188
	v_and_b32_e32 v13, 0x70, v52
	v_bitop3_b32 v0, v180, v12, v13 bitop3:0xde
	v_add_u32_e32 v192, 0, v0
	s_waitcnt lgkmcnt(0)
	s_barrier
	ds_read_b128 v[0:3], v192 offset:32768
	ds_read_b128 v[4:7], v192 offset:40960
	s_waitcnt vmcnt(7) lgkmcnt(1)
	v_mfma_f32_32x32x16_bf16 v[16:31], v[0:3], v[126:129], 0
	v_or_b32_e32 v0, 32, v180
	v_bitop3_b32 v0, v0, v12, v13 bitop3:0xde
	v_add_u32_e32 v201, 0, v0
	v_and_b32_e32 v15, 0xc0, v52
	v_lshlrev_b32_e32 v14, 3, v208
	s_mov_b32 s23, s17
	s_mov_b32 s24, s17
	s_waitcnt lgkmcnt(0)
	v_mfma_f32_32x32x16_bf16 v[32:47], v[4:7], v[126:129], 0
	ds_read_b128 v[0:3], v201 offset:32768
	ds_read_b128 v[4:7], v201 offset:40960
	s_mov_b32 s25, s17
	s_mov_b32 s26, s17
	s_mov_b32 s27, s17
	s_mov_b32 s28, s17
	s_mov_b32 s29, s17
	s_mov_b32 s30, s17
	s_waitcnt vmcnt(6) lgkmcnt(1)
	v_mfma_f32_32x32x16_bf16 v[16:31], v[0:3], v[122:125], v[16:31]
	v_or_b32_e32 v0, 64, v180
	v_bitop3_b32 v0, v0, v12, v13 bitop3:0xde
	v_add_u32_e32 v200, 0, v0
	s_mov_b32 s31, s17
	v_mov_b32_e32 v190, 0
	s_waitcnt lgkmcnt(0)
	v_mfma_f32_32x32x16_bf16 v[32:47], v[4:7], v[122:125], v[32:47]
	ds_read_b128 v[0:3], v200 offset:32768
	ds_read_b128 v[4:7], v200 offset:40960
	s_waitcnt vmcnt(5) lgkmcnt(1)
	v_mfma_f32_32x32x16_bf16 v[16:31], v[0:3], v[134:137], v[16:31]
	v_or_b32_e32 v0, 0x60, v180
	v_bitop3_b32 v0, v0, v12, v13 bitop3:0xde
	v_add_u32_e32 v195, 0, v0
	s_waitcnt lgkmcnt(0)
	v_mfma_f32_32x32x16_bf16 v[32:47], v[4:7], v[134:137], v[32:47]
	ds_read_b128 v[0:3], v195 offset:32768
	ds_read_b128 v[4:7], v195 offset:40960
	s_waitcnt vmcnt(4) lgkmcnt(1)
	v_mfma_f32_32x32x16_bf16 v[16:31], v[0:3], v[130:133], v[16:31]
	v_or_b32_e32 v0, 0x80, v180
	v_bitop3_b32 v0, v0, v12, v13 bitop3:0xde
	v_add_u32_e32 v194, 0, v0
	s_waitcnt lgkmcnt(0)
	v_mfma_f32_32x32x16_bf16 v[32:47], v[4:7], v[130:133], v[32:47]
	ds_read_b128 v[0:3], v194 offset:32768
	ds_read_b128 v[4:7], v194 offset:40960
	s_waitcnt vmcnt(3) lgkmcnt(1)
	v_mfma_f32_32x32x16_bf16 v[16:31], v[0:3], v[118:121], v[16:31]
	v_or_b32_e32 v0, 0xa0, v180
	v_bitop3_b32 v0, v0, v12, v13 bitop3:0xde
	v_add_u32_e32 v193, 0, v0
	ds_read_b128 v[0:3], v193 offset:32768
	s_waitcnt lgkmcnt(1)
; #define SLOAD(i, k0) do { sr_[i].vs0 = St::ld8(&Vh[(long)((k0) + sr) * LDK + sc]); sr_[i].vs1 = St::ld8(&Vh[(long)((k0) + 32 + sr) * LDK + sc]); \
;     sr_[i].ks0 = St::ld8(&Kh[(long)((k0) + sr) * LDK + sc]); sr_[i].ks1 = St::ld8(&Kh[(long)((k0) + 32 + sr) * LDK + sc]); } while (0)
; #define SWAIT() do { if constexpr (SDEPTH == 2) asm volatile("s_waitcnt vmcnt(4)" ::: "memory"); else asm volatile("s_waitcnt vmcnt(0)" ::: "memory"); } while (0)
; __device__ __forceinline__ void partialSM(f32x16& p0, f32x16& p1, float& m_reg, float& mn, float& alpha) {
;   constexpr float C = SCALE * 1.4426950408889634f;
;   float pmax = p0[0]; for (int r = 1; r < 16; ++r) pmax = fmaxf(pmax, p0[r]); for (int r = 0; r < 16; ++r) pmax = fmaxf(pmax, p1[r]);
;   { auto rr = __builtin_amdgcn_permlane32_swap(__float_as_uint(pmax), __float_as_uint(pmax), false, false);
;     pmax = fmaxf(__uint_as_float(rr[0]), __uint_as_float(rr[1])); }
;   if (__builtin_expect(__all(pmax - m_reg <= THR / SCALE), 1)) { mn = m_reg; alpha = 1.f; }
;   else { mn = fmaxf(m_reg, pmax); alpha = __builtin_amdgcn_exp2f((m_reg - mn) * C); m_reg = mn; }
;   float mnC = -mn * C;
;   for (int r = 0; r < 16; ++r) p0[r] = fmaf(p0[r], C, mnC); for (int r = 0; r < 16; ++r) p1[r] = fmaf(p1[r], C, mnC);
;   for (int r = 0; r < 16; ++r) p0[r] = __builtin_amdgcn_exp2f(p0[r]);
; }
; __device__ __forceinline__ void attn_dense_body(const bf16* __restrict__ Qb, const bf16* __restrict__ Kh, const bf16* __restrict__ Vh,
;                                                 const unsigned short* __restrict__ Gb, unsigned short* __restrict__ Yb, int seq, char* lds, const int tid) {
;     ...
;   SLOAD(SE, 0); asm volatile("s_waitcnt vmcnt(0)" ::: "memory"); SWRITE(0, SE); __syncthreads();
;   qkt(pA0, pA1, K_lds, qr, r32, hi); partialSM(pA0, pA1, m_reg, mnA, alA);
;   SLOAD(SO, KVBLK); if constexpr (SDEPTH == 2) { if (2 < NT) SLOAD(SE, 2 * KVBLK); }
;   SWAIT(); SWRITE(1, SO); __syncthreads();
	v_mfma_f32_32x32x16_bf16 v[32:47], v[4:7], v[118:121], v[32:47]
	v_and_b32_e32 v4, 0x3fffffc0, v74
	v_lshl_add_u32 v181, v4, 2, s12
	s_mov_b64 s[12:13], 0x10000
	ds_read_b128 v[4:7], v193 offset:40960
	v_lshl_add_u32 v189, v188, 2, v181
	s_waitcnt vmcnt(2) lgkmcnt(1)
	v_mfma_f32_32x32x16_bf16 v[16:31], v[0:3], v[114:117], v[16:31]
	v_lshl_add_u64 v[0:1], v[50:51], 0, s[12:13]
	s_mov_b64 s[12:13], 0x18000
	v_lshl_add_u64 v[2:3], s[8:9], 0, v[0:1]
	v_lshl_add_u64 v[8:9], v[50:51], 0, s[12:13]
	v_lshl_add_u64 v[0:1], s[6:7], 0, v[0:1]
	v_lshl_add_u64 v[10:11], s[8:9], 0, v[8:9]
	global_load_dwordx4 v[52:55], v[2:3], off
	global_load_dwordx4 v[56:59], v[10:11], off
	v_lshl_add_u64 v[2:3], s[6:7], 0, v[8:9]
	global_load_dwordx4 v[60:63], v[0:1], off
	global_load_dwordx4 v[64:67], v[2:3], off
	v_or_b32_e32 v0, 0xc0, v180
	v_bitop3_b32 v0, v0, v12, v13 bitop3:0xde
	v_add_u32_e32 v207, 0, v0
	ds_read_b128 v[0:3], v207 offset:32768
	v_lshlrev_b32_e32 v9, 1, v74
	v_and_or_b32 v8, v14, 24, v15
	s_waitcnt lgkmcnt(1)
	v_mfma_f32_32x32x16_bf16 v[32:47], v[4:7], v[114:117], v[32:47]
	v_and_b32_e32 v4, 32, v9
	v_and_b32_e32 v5, 0x100, v14
	v_or3_b32 v75, v8, v4, v5
	ds_read_b128 v[4:7], v207 offset:40960
	s_mov_b64 s[12:13], 0x28000
	v_add_u32_e32 v179, s51, v75
	s_waitcnt vmcnt(5) lgkmcnt(1)
	v_mfma_f32_32x32x16_bf16 v[16:31], v[0:3], v[110:113], v[16:31]
	v_or_b32_e32 v0, 0xe0, v180
	v_bitop3_b32 v0, v0, v12, v13 bitop3:0xde
	v_add_u32_e32 v206, 0, v0
	ds_read_b128 v[0:3], v206 offset:32768
	ds_read_b128 v[68:71], v206 offset:40960
	s_waitcnt lgkmcnt(2)
	v_mfma_f32_32x32x16_bf16 v[32:47], v[4:7], v[110:113], v[32:47]
	s_waitcnt vmcnt(4) lgkmcnt(1)
	v_mfma_f32_32x32x16_bf16 v[16:31], v[0:3], v[106:109], v[16:31]
	v_mov_b64_e32 v[0:1], s[16:17]
	v_mov_b64_e32 v[14:15], s[30:31]
	v_mov_b64_e32 v[2:3], s[18:19]
	v_mov_b64_e32 v[4:5], s[20:21]
	v_mov_b64_e32 v[6:7], s[22:23]
	v_mov_b64_e32 v[8:9], s[24:25]
	v_mov_b64_e32 v[10:11], s[26:27]
	s_waitcnt lgkmcnt(0)
	v_mfma_f32_32x32x16_bf16 v[32:47], v[68:71], v[106:109], v[32:47]
	s_nop 2
	v_max_f32_e32 v68, v17, v17
	v_max_f32_e32 v69, v16, v16
	v_max_f32_e32 v68, v69, v68
	v_max3_f32 v68, v68, v18, v19
	v_max3_f32 v68, v68, v20, v21
	v_max3_f32 v68, v68, v22, v23
	v_max3_f32 v68, v68, v24, v25
	v_max3_f32 v68, v68, v26, v27
	v_max3_f32 v68, v68, v28, v29
	v_max3_f32 v68, v68, v30, v31
	v_max3_f32 v68, v68, v32, v33
	v_max3_f32 v68, v68, v34, v35
	v_max3_f32 v68, v68, v36, v37
	v_max3_f32 v68, v68, v38, v39
	v_max3_f32 v68, v68, v40, v41
	v_max3_f32 v68, v68, v42, v43
	v_max3_f32 v68, v68, v44, v45
	v_max3_f32 v76, v68, v46, v47
	v_lshl_add_u64 v[68:69], v[50:51], 0, s[82:83]
	v_lshl_add_u64 v[70:71], s[8:9], 0, v[68:69]
	v_lshl_add_u64 v[50:51], v[50:51], 0, s[12:13]
	v_lshl_add_u64 v[68:69], s[6:7], 0, v[68:69]
	v_lshl_add_u64 v[72:73], s[8:9], 0, v[50:51]
	global_load_dwordx4 v[98:101], v[70:71], off
	global_load_dwordx4 v[138:141], v[72:73], off
	v_lshl_add_u64 v[50:51], s[6:7], 0, v[50:51]
	global_load_dwordx4 v[102:105], v[68:69], off
	global_load_dwordx4 v[142:145], v[50:51], off
	v_mov_b32_e32 v50, v76
	s_nop 1
	v_permlane32_swap_b32_e32 v76, v50
	v_max_f32_e32 v50, v50, v50
	v_max_f32_e32 v51, v76, v76
	v_max_f32_e32 v50, v51, v50
	v_add_f32_e32 v51, 0x7149f2ca, v50
	v_cmp_ge_f32_e32 vcc, s68, v51
	s_cmp_eq_u64 vcc, exec
	v_max_f32_e32 v50, 0xf149f2ca, v50
	s_cselect_b64 vcc, -1, 0
	v_cndmask_b32_e32 v210, v50, v239, vcc
	v_sub_f32_e32 v51, 0xf149f2ca, v50
	v_mul_f32_e32 v50, 0xbe0293ee, v210
	v_fmamk_f32 v16, v16, 0x3e0293ee, v50
	v_exp_f32_e32 v223, v16
	v_fmamk_f32 v16, v17, 0x3e0293ee, v50
	v_exp_f32_e32 v224, v16
	v_fmamk_f32 v16, v18, 0x3e0293ee, v50
	v_exp_f32_e32 v225, v16
	v_fmamk_f32 v16, v19, 0x3e0293ee, v50
	v_exp_f32_e32 v227, v16
	v_fmamk_f32 v16, v20, 0x3e0293ee, v50
	v_exp_f32_e32 v229, v16
	v_fmamk_f32 v16, v21, 0x3e0293ee, v50
	v_exp_f32_e32 v230, v16
	v_fmamk_f32 v16, v22, 0x3e0293ee, v50
	v_exp_f32_e32 v226, v16
	v_fmamk_f32 v16, v23, 0x3e0293ee, v50
	v_exp_f32_e32 v228, v16
	v_fmamk_f32 v16, v24, 0x3e0293ee, v50
	v_mul_f32_e32 v51, 0x3e0293ee, v51
	v_exp_f32_e32 v215, v16
	v_fmamk_f32 v16, v25, 0x3e0293ee, v50
	v_exp_f32_e32 v51, v51
	v_exp_f32_e32 v217, v16
	v_fmamk_f32 v16, v26, 0x3e0293ee, v50
	v_exp_f32_e32 v219, v16
	v_fmamk_f32 v16, v27, 0x3e0293ee, v50
	v_exp_f32_e32 v221, v16
	v_fmamk_f32 v16, v28, 0x3e0293ee, v50
	v_exp_f32_e32 v216, v16
	v_fmamk_f32 v16, v29, 0x3e0293ee, v50
	v_pk_fma_f32 v[162:163], v[46:47], s[84:85], v[50:51] op_sel_hi:[1,0,0]
	v_pk_fma_f32 v[168:169], v[44:45], s[84:85], v[50:51] op_sel_hi:[1,0,0]
	v_pk_fma_f32 v[172:173], v[42:43], s[84:85], v[50:51] op_sel_hi:[1,0,0]
	v_pk_fma_f32 v[164:165], v[40:41], s[84:85], v[50:51] op_sel_hi:[1,0,0]
	v_pk_fma_f32 v[166:167], v[38:39], s[84:85], v[50:51] op_sel_hi:[1,0,0]
	v_pk_fma_f32 v[170:171], v[36:37], s[84:85], v[50:51] op_sel_hi:[1,0,0]
	v_pk_fma_f32 v[174:175], v[34:35], s[84:85], v[50:51] op_sel_hi:[1,0,0]
	v_pk_fma_f32 v[176:177], v[32:33], s[84:85], v[50:51] op_sel_hi:[1,0,0]
	v_exp_f32_e32 v218, v16
	v_fmamk_f32 v16, v30, 0x3e0293ee, v50
	v_fmac_f32_e32 v50, 0x3e0293ee, v31
	v_and_b32_e32 v18, 15, v74
	v_exp_f32_e32 v220, v16
	v_exp_f32_e32 v222, v50
	v_mad_i64_i32 v[16:17], s[8:9], s48, v240, v[48:49]
	v_lshlrev_b32_e32 v18, 4, v18
	s_waitcnt vmcnt(4)
	v_or3_b32 v16, v16, s49, v18
	v_mov_b64_e32 v[12:13], s[28:29]
	s_waitcnt vmcnt(7)
	ds_write_b128 v204, v[52:55] offset:16384
	s_waitcnt vmcnt(6)
	ds_write_b128 v205, v[56:59] offset:16384
	s_waitcnt vmcnt(5)
	ds_write_b128 v202, v[60:63] offset:49152
	s_waitcnt vmcnt(4)
; #define SBAR() __builtin_amdgcn_sched_barrier(0)
; #define SLOAD(i, k0) do { sr_[i].vs0 = St::ld8(&Vh[(long)((k0) + sr) * LDK + sc]); sr_[i].vs1 = St::ld8(&Vh[(long)((k0) + 32 + sr) * LDK + sc]); \
;     sr_[i].ks0 = St::ld8(&Kh[(long)((k0) + sr) * LDK + sc]); sr_[i].ks1 = St::ld8(&Kh[(long)((k0) + 32 + sr) * LDK + sc]); } while (0)
; __device__ __forceinline__ void finishSM(f32x16& p0, f32x16& p1, float alpha, float& l_reg, bf16x8& pa0, bf16x8& pa1, bf16x8& pa2, bf16x8& pa3) {
;   for (int r = 0; r < 16; ++r) p1[r] = __builtin_amdgcn_exp2f(p1[r]);
;   float ps = 0; for (int r = 0; r < 16; ++r) ps += p0[r]; for (int r = 0; r < 16; ++r) ps += p1[r];
;   { auto rr = __builtin_amdgcn_permlane32_swap(__float_as_uint(ps), __float_as_uint(ps), false, false);
;     ps = __uint_as_float(rr[0]) + __uint_as_float(rr[1]); }
;   l_reg = l_reg * alpha + ps;
;     ...
;   PK4(p0, 0, pa0); PK4(p0, 8, pa1); PK4(p1, 0, pa2); PK4(p1, 8, pa3);
;     ...
; }
; __device__ __forceinline__ void qkt(f32x16& p0, f32x16& p1, const bf16* Ks, const bf16x8* qr, int r32, int hi) {
;   p0 = f32x16{}; p1 = f32x16{};
;   for (int d0 = 0; d0 < 8; ++d0) { int cb = (d0 * 16 + hi * 8) * 2;
;     bf16x8 b0 = *reinterpret_cast<const bf16x8*>((const char*)Ks + KSWZ(r32, cb));
;     bf16x8 b1 = *reinterpret_cast<const bf16x8*>((const char*)Ks + KSWZ(32 + r32, cb));
;     p0 = __builtin_amdgcn_mfma_f32_32x32x16_bf16(b0, qr[d0], p0, 0, 0, 0);
;     p1 = __builtin_amdgcn_mfma_f32_32x32x16_bf16(b1, qr[d0], p1, 0, 0, 0); }
; }
; __device__ __forceinline__ void attn_dense_body(const bf16* __restrict__ Qb, const bf16* __restrict__ Kh, const bf16* __restrict__ Vh,
;                                                 const unsigned short* __restrict__ Gb, unsigned short* __restrict__ Yb, int seq, char* lds, const int tid) {
;     ...
;     SBAR(); qkt(pB0, pB1, (bf16*)((char*)K_lds + SHM_K), qr, r32, hi);
;     finishSM(pA0, pA1, alA, l_reg, pa0, pa1, pa2, pa3); SBAR();
;     SLOAD(SO, (j + SDEPTH) * KVBLK); SBAR();
	ds_write_b128 v203, v[64:67] offset:49152
	v_cndmask_b32_e64 v209, v51, 1.0, vcc
	s_addk_i32 s51, 0x4000
	v_lshl_add_u64 v[182:183], s[10:11], 0, v[16:17]
	v_mov_b64_e32 v[62:63], v[14:15]
	v_mov_b64_e32 v[46:47], v[14:15]
	v_mov_b64_e32 v[30:31], v[14:15]
	v_cmp_gt_u32_e64 s[6:7], 32, v208
	v_add_u32_e32 v191, s51, v75
	v_mov_b64_e32 v[60:61], v[12:13]
	v_mov_b64_e32 v[58:59], v[10:11]
	v_mov_b64_e32 v[56:57], v[8:9]
	v_mov_b64_e32 v[54:55], v[6:7]
	v_mov_b64_e32 v[52:53], v[4:5]
	v_mov_b64_e32 v[50:51], v[2:3]
	v_mov_b64_e32 v[48:49], v[0:1]
	v_mov_b64_e32 v[44:45], v[12:13]
	v_mov_b64_e32 v[42:43], v[10:11]
	v_mov_b64_e32 v[40:41], v[8:9]
	v_mov_b64_e32 v[38:39], v[6:7]
	v_mov_b64_e32 v[36:37], v[4:5]
	v_mov_b64_e32 v[34:35], v[2:3]
	v_mov_b64_e32 v[32:33], v[0:1]
	v_mov_b64_e32 v[28:29], v[12:13]
	v_mov_b64_e32 v[26:27], v[10:11]
	v_mov_b64_e32 v[24:25], v[8:9]
	v_mov_b64_e32 v[22:23], v[6:7]
	v_mov_b64_e32 v[20:21], v[4:5]
	v_mov_b64_e32 v[18:19], v[2:3]
	v_mov_b64_e32 v[16:17], v[0:1]
	v_mbcnt_lo_u32_b32 v232, -1, 0
	v_mbcnt_hi_u32_b32 v232, -1, v232
	v_and_b32_e32 v233, 15, v232
	v_lshrrev_b32_e32 v232, 4, v232
	v_xor_b32_e32 v251, v233, v232
	v_or_b32_e32 v232, 4, v232
	v_xor_b32_e32 v255, v233, v232
	v_sub_u32_e32 v251, v251, v233
	v_sub_u32_e32 v255, v255, v233
	v_lshlrev_b32_e32 v251, 4, v251
	v_lshlrev_b32_e32 v255, 4, v255
	s_lshl_b32 s8, s65, 6
	s_add_i32 s8, s8, 0xff6d8000
	v_add_u32_e32 v251, s8, v251
	s_addk_i32 s8, 0x1000
	v_add_u32_e32 v255, s8, v255
	s_waitcnt lgkmcnt(0)
	s_barrier
.LBB0_602:
	s_lshl_b32 s8, s65, 5
	v_add_co_u32_e32 v232, vcc, v251, v182
	s_add_i32 m0, s8, 0x8000
	s_nop 0
	v_addc_co_u32_e32 v233, vcc, -1, v183, vcc
	global_load_lds_dwordx4 v[232:233], off
	v_add_co_u32_e32 v232, vcc, v255, v182
	s_add_i32 m0, s8, 0x8400
	s_nop 0
	v_addc_co_u32_e32 v233, vcc, -1, v183, vcc
	global_load_lds_dwordx4 v[232:233], off
	ds_read_b128 v[64:67], v192 offset:49152
	ds_read_b128 v[68:71], v192 offset:57344
	ds_read_b128 v[242:245], v201 offset:49152
	ds_read_b128 v[246:249], v201 offset:57344
	v_exp_f32_e32 v160, v162
	v_add_f32_e32 v162, 0, v223
	s_waitcnt lgkmcnt(3)
	v_mfma_f32_32x32x16_bf16 v[80:95], v[64:67], v[126:129], 0
	v_add_f32_e32 v162, v224, v162
	v_add_f32_e32 v162, v225, v162
	v_add_f32_e32 v162, v227, v162
	v_add_f32_e32 v162, v229, v162
	v_add_f32_e32 v162, v230, v162
	v_add_f32_e32 v162, v226, v162
	v_add_f32_e32 v162, v228, v162
	s_waitcnt lgkmcnt(2)
	v_mfma_f32_32x32x16_bf16 v[64:79], v[68:71], v[126:129], 0
	v_add_f32_e32 v162, v215, v162
	v_add_f32_e32 v162, v217, v162
	v_add_f32_e32 v162, v219, v162
	v_add_f32_e32 v162, v221, v162
	v_add_f32_e32 v162, v216, v162
	v_add_f32_e32 v162, v218, v162
	v_add_f32_e32 v162, v220, v162
	s_waitcnt lgkmcnt(1)
	v_mfma_f32_32x32x16_bf16 v[80:95], v[242:245], v[122:125], v[80:95]
	v_add_f32_e32 v162, v222, v162
	v_exp_f32_e32 v154, v164
	v_exp_f32_e32 v155, v165
	v_exp_f32_e32 v156, v172
	v_exp_f32_e32 v157, v173
	v_exp_f32_e32 v158, v168
	v_exp_f32_e32 v159, v169
	s_waitcnt lgkmcnt(0)
	v_mfma_f32_32x32x16_bf16 v[64:79], v[246:249], v[122:125], v[64:79]
	ds_read_b128 v[242:245], v200 offset:49152
	ds_read_b128 v[246:249], v200 offset:57344
	v_exp_f32_e32 v161, v163
	v_cvt_pk_bf16_f32 v164, v229, v230
	v_cvt_pk_bf16_f32 v163, v225, v227
	v_cvt_pk_bf16_f32 v165, v226, v228
	v_cvt_pk_bf16_f32 v168, v216, v218
	v_cvt_pk_bf16_f32 v169, v220, v222
	s_waitcnt lgkmcnt(1)
	v_mfma_f32_32x32x16_bf16 v[80:95], v[242:245], v[134:137], v[80:95]
	v_exp_f32_e32 v146, v176
	v_exp_f32_e32 v147, v177
	v_exp_f32_e32 v148, v174
	v_exp_f32_e32 v149, v175
	v_permlane32_swap_b32_e32 v163, v165
	s_waitcnt lgkmcnt(0)
	v_mfma_f32_32x32x16_bf16 v[64:79], v[246:249], v[134:137], v[64:79]
	ds_read_b128 v[242:245], v195 offset:49152
	ds_read_b128 v[246:249], v195 offset:57344
	v_add_f32_e32 v162, v146, v162
	v_add_f32_e32 v162, v147, v162
	v_add_f32_e32 v162, v148, v162
	v_exp_f32_e32 v150, v170
	s_waitcnt lgkmcnt(1)
	v_mfma_f32_32x32x16_bf16 v[80:95], v[242:245], v[130:133], v[80:95]
	v_exp_f32_e32 v151, v171
	v_exp_f32_e32 v152, v166
	v_exp_f32_e32 v153, v167
	v_add_f32_e32 v162, v149, v162
	s_waitcnt lgkmcnt(0)
	v_mfma_f32_32x32x16_bf16 v[64:79], v[246:249], v[130:133], v[64:79]
	ds_read_b128 v[242:245], v194 offset:49152
	ds_read_b128 v[246:249], v194 offset:57344
	v_add_f32_e32 v162, v150, v162
	v_add_f32_e32 v162, v151, v162
	v_add_f32_e32 v162, v152, v162
	v_add_f32_e32 v162, v153, v162
	s_waitcnt lgkmcnt(1)
	v_mfma_f32_32x32x16_bf16 v[80:95], v[242:245], v[118:121], v[80:95]
	v_add_f32_e32 v162, v154, v162
	v_add_f32_e32 v162, v155, v162
	v_add_f32_e32 v162, v156, v162
	v_add_f32_e32 v162, v157, v162
	s_waitcnt lgkmcnt(0)
	v_mfma_f32_32x32x16_bf16 v[64:79], v[246:249], v[118:121], v[64:79]
	ds_read_b128 v[242:245], v193 offset:49152
	ds_read_b128 v[246:249], v193 offset:57344
	v_add_f32_e32 v162, v158, v162
	v_add_f32_e32 v162, v159, v162
	v_add_f32_e32 v162, v160, v162
	v_add_f32_e32 v211, v161, v162
	s_waitcnt lgkmcnt(1)
	v_mfma_f32_32x32x16_bf16 v[80:95], v[242:245], v[114:117], v[80:95]
	v_mov_b32_e32 v212, v211
	v_cvt_pk_bf16_f32 v162, v223, v224
	s_nop 0
	v_permlane32_swap_b32_e32 v211, v212
	s_waitcnt lgkmcnt(0)
	v_mfma_f32_32x32x16_bf16 v[64:79], v[246:249], v[114:117], v[64:79]
	ds_read_b128 v[242:245], v207 offset:49152
	ds_read_b128 v[246:249], v207 offset:57344
	v_permlane32_swap_b32_e32 v162, v164
	v_cvt_pk_bf16_f32 v166, v215, v217
	v_cvt_pk_bf16_f32 v167, v219, v221
	v_cvt_pk_bf16_f32 v170, v146, v147
	s_waitcnt lgkmcnt(1)
	v_mfma_f32_32x32x16_bf16 v[80:95], v[242:245], v[110:113], v[80:95]
	v_cvt_pk_bf16_f32 v171, v148, v149
	v_cvt_pk_bf16_f32 v172, v150, v151
	v_cvt_pk_bf16_f32 v173, v152, v153
	v_cvt_pk_bf16_f32 v174, v154, v155
	s_waitcnt lgkmcnt(0)
; #define SBAR() __builtin_amdgcn_sched_barrier(0)
; __device__ __forceinline__ void partialSM(f32x16& p0, f32x16& p1, float& m_reg, float& mn, float& alpha) {
;   constexpr float C = SCALE * 1.4426950408889634f;
;   float pmax = p0[0]; for (int r = 1; r < 16; ++r) pmax = fmaxf(pmax, p0[r]); for (int r = 0; r < 16; ++r) pmax = fmaxf(pmax, p1[r]);
;   { auto rr = __builtin_amdgcn_permlane32_swap(__float_as_uint(pmax), __float_as_uint(pmax), false, false);
;     pmax = fmaxf(__uint_as_float(rr[0]), __uint_as_float(rr[1])); }
;   if (__builtin_expect(__all(pmax - m_reg <= THR / SCALE), 1)) { mn = m_reg; alpha = 1.f; }
;   else { mn = fmaxf(m_reg, pmax); alpha = __builtin_amdgcn_exp2f((m_reg - mn) * C); m_reg = mn; }
;   float mnC = -mn * C;
;   for (int r = 0; r < 16; ++r) p0[r] = fmaf(p0[r], C, mnC); for (int r = 0; r < 16; ++r) p1[r] = fmaf(p1[r], C, mnC);
;   for (int r = 0; r < 16; ++r) p0[r] = __builtin_amdgcn_exp2f(p0[r]);
; }
; template <int D0> __device__ __forceinline__ void pv_one(f32x16& od, int vb, bf16x8 pa0, bf16x8 pa1, bf16x8 pa2, bf16x8 pa3) {
;   const s16x4 l0 = tr_read<v_rd_off(D0, 0, 0)>(vb), h0 = tr_read<v_rd_off(D0, 0, 1)>(vb), l1 = tr_read<v_rd_off(D0, 1, 0)>(vb), h1 = tr_read<v_rd_off(D0, 1, 1)>(vb);
;   const s16x4 l2 = tr_read<v_rd_off(D0, 2, 0)>(vb), h2 = tr_read<v_rd_off(D0, 2, 1)>(vb), l3 = tr_read<v_rd_off(D0, 3, 0)>(vb), h3 = tr_read<v_rd_off(D0, 3, 1)>(vb);
;   asm volatile("s_waitcnt lgkmcnt(0)" ::: "memory"); SBAR();
;     ...
;   od = __builtin_amdgcn_mfma_f32_32x32x16_bf16(pa0, PK(l0, h0), od, 0, 0, 0);
;   od = __builtin_amdgcn_mfma_f32_32x32x16_bf16(pa1, PK(l1, h1), od, 0, 0, 0);
;   od = __builtin_amdgcn_mfma_f32_32x32x16_bf16(pa2, PK(l2, h2), od, 0, 0, 0);
;   od = __builtin_amdgcn_mfma_f32_32x32x16_bf16(pa3, PK(l3, h3), od, 0, 0, 0);
;     ...
; }
; __device__ __forceinline__ void pv_d0(f32x16* o, int vb, bf16x8 pa0, bf16x8 pa1, bf16x8 pa2, bf16x8 pa3) {
;   pv_one<0>(o[0], vb, pa0, pa1, pa2, pa3); pv_one<1>(o[1], vb, pa0, pa1, pa2, pa3); pv_one<2>(o[2], vb, pa0, pa1, pa2, pa3); pv_one<3>(o[3], vb, pa0, pa1, pa2, pa3);
	v_mfma_f32_32x32x16_bf16 v[64:79], v[246:249], v[110:113], v[64:79]
	ds_read_b128 v[242:245], v206 offset:49152
	ds_read_b128 v[246:249], v206 offset:57344
	v_cvt_pk_bf16_f32 v175, v156, v157
	v_cvt_pk_bf16_f32 v176, v158, v159
	v_cvt_pk_bf16_f32 v177, v160, v161
	s_waitcnt lgkmcnt(1)
	v_mfma_f32_32x32x16_bf16 v[80:95], v[242:245], v[106:109], v[80:95]
	v_permlane32_swap_b32_e32 v166, v168
	v_permlane32_swap_b32_e32 v167, v169
	v_permlane32_swap_b32_e32 v170, v172
	s_waitcnt lgkmcnt(0)
	v_mfma_f32_32x32x16_bf16 v[64:79], v[246:249], v[106:109], v[64:79]
	v_permlane32_swap_b32_e32 v171, v173
	v_permlane32_swap_b32_e32 v174, v176
	v_permlane32_swap_b32_e32 v175, v177
	v_add_co_u32_e32 v146, vcc, s69, v182
	s_mov_b32 s8, 0xffff0000
	s_nop 0
	v_addc_co_u32_e32 v147, vcc, -1, v183, vcc
	v_add_co_u32_e32 v150, vcc, s8, v182
	s_nop 1
	v_addc_co_u32_e32 v151, vcc, -1, v183, vcc
	global_load_dwordx4 v[146:149], v[146:147], off
	s_nop 0
	global_load_dwordx4 v[150:153], v[150:151], off
	ds_read_b64_tr_b16 v[214:215], v179 offset:0
	ds_read_b64_tr_b16 v[216:217], v179 offset:0x800
	ds_read_b64_tr_b16 v[218:219], v179 offset:0x1000
	ds_read_b64_tr_b16 v[220:221], v179 offset:0x1800
	ds_read_b64_tr_b16 v[222:223], v179 offset:0x2000
	ds_read_b64_tr_b16 v[224:225], v179 offset:0x2800
	ds_read_b64_tr_b16 v[226:227], v179 offset:0x3000
	ds_read_b64_tr_b16 v[228:229], v179 offset:0x3800
	s_waitcnt lgkmcnt(0)
	s_nop 0
	v_mfma_f32_32x32x16_bf16 v[0:15], v[162:165], v[214:217], v[0:15]
	ds_read_b64_tr_b16 v[214:215], v179 offset:0x200
	ds_read_b64_tr_b16 v[216:217], v179 offset:0xa00
	v_max_f32_e32 v232, v81, v81
	v_max_f32_e32 v233, v80, v80
	v_max_f32_e32 v232, v233, v232
	v_max3_f32 v232, v232, v82, v83
	v_max3_f32 v232, v232, v84, v85
	v_max3_f32 v232, v232, v86, v87
	v_mfma_f32_32x32x16_bf16 v[0:15], v[166:169], v[218:221], v[0:15]
	ds_read_b64_tr_b16 v[218:219], v179 offset:0x1200
	ds_read_b64_tr_b16 v[220:221], v179 offset:0x1a00
	v_max3_f32 v232, v232, v88, v89
	v_max3_f32 v232, v232, v90, v91
	v_max3_f32 v232, v232, v92, v93
	v_max3_f32 v232, v232, v94, v95
	v_max3_f32 v232, v232, v64, v65
	v_max3_f32 v232, v232, v66, v67
	v_mfma_f32_32x32x16_bf16 v[0:15], v[170:173], v[222:225], v[0:15]
	ds_read_b64_tr_b16 v[222:223], v179 offset:0x2200
	ds_read_b64_tr_b16 v[224:225], v179 offset:0x2a00
	v_max3_f32 v232, v232, v68, v69
	v_max3_f32 v232, v232, v70, v71
	v_max3_f32 v232, v232, v72, v73
	v_max3_f32 v232, v232, v74, v75
	v_max3_f32 v232, v232, v76, v77
	v_max3_f32 v232, v232, v78, v79
	v_mfma_f32_32x32x16_bf16 v[0:15], v[174:177], v[226:229], v[0:15]
	ds_read_b64_tr_b16 v[226:227], v179 offset:0x3200
	ds_read_b64_tr_b16 v[228:229], v179 offset:0x3a00
	v_mov_b32_e32 v233, v232
	s_nop 1
	v_permlane32_swap_b32_e32 v232, v233
	v_max_f32_e32 v233, v233, v233
	v_max_f32_e32 v232, v232, v232
	v_max_f32_e32 v232, v232, v233
	s_waitcnt lgkmcnt(0)
	v_mfma_f32_32x32x16_bf16 v[48:63], v[162:165], v[214:217], v[48:63]
	ds_read_b64_tr_b16 v[214:215], v179 offset:0x400
	ds_read_b64_tr_b16 v[216:217], v179 offset:0xc00
	v_sub_f32_e32 v233, v232, v210
	v_cmp_ge_f32_e32 vcc, s68, v233
	v_max_f32_e32 v233, v210, v210
	v_max_f32_e32 v232, v233, v232
	v_sub_f32_e32 v233, v210, v232
	v_mul_f32_e32 v233, 0x3e0293ee, v233
	v_mfma_f32_32x32x16_bf16 v[48:63], v[166:169], v[218:221], v[48:63]
	ds_read_b64_tr_b16 v[218:219], v179 offset:0x1400
	ds_read_b64_tr_b16 v[220:221], v179 offset:0x1c00
	s_cmp_eq_u64 vcc, exec
	s_cselect_b64 s[8:9], -1, 0
	v_exp_f32_e32 v233, v233
	v_mfma_f32_32x32x16_bf16 v[48:63], v[170:173], v[222:225], v[48:63]
	ds_read_b64_tr_b16 v[222:223], v179 offset:0x2400
	ds_read_b64_tr_b16 v[224:225], v179 offset:0x2c00
	v_cndmask_b32_e64 v210, v232, v210, s[8:9]
	v_mul_f32_e32 v213, 0xbe0293ee, v210
	v_fmamk_f32 v80, v80, 0x3e0293ee, v213
	v_fmamk_f32 v81, v81, 0x3e0293ee, v213
	v_fmamk_f32 v82, v82, 0x3e0293ee, v213
	v_fmamk_f32 v83, v83, 0x3e0293ee, v213
	v_mfma_f32_32x32x16_bf16 v[48:63], v[174:177], v[226:229], v[48:63]
	ds_read_b64_tr_b16 v[226:227], v179 offset:0x3400
	ds_read_b64_tr_b16 v[228:229], v179 offset:0x3c00
	v_fmamk_f32 v84, v84, 0x3e0293ee, v213
	v_fmamk_f32 v85, v85, 0x3e0293ee, v213
	v_fmamk_f32 v86, v86, 0x3e0293ee, v213
	v_fmamk_f32 v87, v87, 0x3e0293ee, v213
	v_fmamk_f32 v88, v88, 0x3e0293ee, v213
	v_fmamk_f32 v89, v89, 0x3e0293ee, v213
	s_waitcnt lgkmcnt(0)
	v_mfma_f32_32x32x16_bf16 v[32:47], v[162:165], v[214:217], v[32:47]
	ds_read_b64_tr_b16 v[214:215], v179 offset:0x600
	ds_read_b64_tr_b16 v[216:217], v179 offset:0xe00
	v_fmamk_f32 v90, v90, 0x3e0293ee, v213
	v_fmamk_f32 v91, v91, 0x3e0293ee, v213
	v_fmamk_f32 v92, v92, 0x3e0293ee, v213
	v_fmamk_f32 v93, v93, 0x3e0293ee, v213
	v_fmamk_f32 v94, v94, 0x3e0293ee, v213
	v_fmamk_f32 v95, v95, 0x3e0293ee, v213
	v_mfma_f32_32x32x16_bf16 v[32:47], v[166:169], v[218:221], v[32:47]
	ds_read_b64_tr_b16 v[218:219], v179 offset:0x1600
	ds_read_b64_tr_b16 v[220:221], v179 offset:0x1e00
	v_exp_f32_e32 v80, v80
	v_exp_f32_e32 v81, v81
	v_exp_f32_e32 v82, v82
	v_mfma_f32_32x32x16_bf16 v[32:47], v[170:173], v[222:225], v[32:47]
	ds_read_b64_tr_b16 v[222:223], v179 offset:0x2600
	ds_read_b64_tr_b16 v[224:225], v179 offset:0x2e00
	v_exp_f32_e32 v83, v83
	v_exp_f32_e32 v84, v84
	v_exp_f32_e32 v85, v85
	v_mfma_f32_32x32x16_bf16 v[32:47], v[174:177], v[226:229], v[32:47]
	ds_read_b64_tr_b16 v[226:227], v179 offset:0x3600
	ds_read_b64_tr_b16 v[228:229], v179 offset:0x3e00
	v_exp_f32_e32 v86, v86
	v_exp_f32_e32 v87, v87
	v_exp_f32_e32 v88, v88
	s_waitcnt lgkmcnt(0)
	v_mfma_f32_32x32x16_bf16 v[16:31], v[162:165], v[214:217], v[16:31]
	v_exp_f32_e32 v89, v89
	v_exp_f32_e32 v90, v90
	v_exp_f32_e32 v91, v91
	v_mfma_f32_32x32x16_bf16 v[16:31], v[166:169], v[218:221], v[16:31]
	v_exp_f32_e32 v92, v92
	v_exp_f32_e32 v93, v93
	v_mfma_f32_32x32x16_bf16 v[16:31], v[170:173], v[222:225], v[16:31]
	v_exp_f32_e32 v94, v94
	v_exp_f32_e32 v95, v95
	v_mfma_f32_32x32x16_bf16 v[16:31], v[174:177], v[226:229], v[16:31]
	s_waitcnt vmcnt(2)
	s_barrier
; __device__ __forceinline__ void partialSM(f32x16& p0, f32x16& p1, float& m_reg, float& mn, float& alpha) {
;     ...
;   float mnC = -mn * C;
;   for (int r = 0; r < 16; ++r) p0[r] = fmaf(p0[r], C, mnC); for (int r = 0; r < 16; ++r) p1[r] = fmaf(p1[r], C, mnC);
;   for (int r = 0; r < 16; ++r) p0[r] = __builtin_amdgcn_exp2f(p0[r]);
; }
; __device__ __forceinline__ void finishSM(f32x16& p0, f32x16& p1, float alpha, float& l_reg, bf16x8& pa0, bf16x8& pa1, bf16x8& pa2, bf16x8& pa3) {
;   for (int r = 0; r < 16; ++r) p1[r] = __builtin_amdgcn_exp2f(p1[r]);
;   float ps = 0; for (int r = 0; r < 16; ++r) ps += p0[r]; for (int r = 0; r < 16; ++r) ps += p1[r];
;   { auto rr = __builtin_amdgcn_permlane32_swap(__float_as_uint(ps), __float_as_uint(ps), false, false);
;     ps = __uint_as_float(rr[0]) + __uint_as_float(rr[1]); }
;   l_reg = l_reg * alpha + ps;
;     ...
;   PK4(p0, 0, pa0); PK4(p0, 8, pa1); PK4(p1, 0, pa2); PK4(p1, 8, pa3);
;     ...
; }
; __device__ __forceinline__ void qkt(f32x16& p0, f32x16& p1, const bf16* Ks, const bf16x8* qr, int r32, int hi) {
;   p0 = f32x16{}; p1 = f32x16{};
;   for (int d0 = 0; d0 < 8; ++d0) { int cb = (d0 * 16 + hi * 8) * 2;
;     bf16x8 b0 = *reinterpret_cast<const bf16x8*>((const char*)Ks + KSWZ(r32, cb));
;     bf16x8 b1 = *reinterpret_cast<const bf16x8*>((const char*)Ks + KSWZ(32 + r32, cb));
;     p0 = __builtin_amdgcn_mfma_f32_32x32x16_bf16(b0, qr[d0], p0, 0, 0, 0);
;     p1 = __builtin_amdgcn_mfma_f32_32x32x16_bf16(b1, qr[d0], p1, 0, 0, 0); }
; }
	s_waitcnt vmcnt(4)
	v_cndmask_b32_e64 v214, v233, 1.0, s[8:9]
	v_cmp_gt_f32_e32 vcc, 1.0, v214
	s_waitcnt vmcnt(7)
	ds_write_b128 v204, v[98:101]
	s_waitcnt vmcnt(6)
	ds_write_b128 v205, v[138:141]
	s_cbranch_vccz .LBB0_606
	s_and_saveexec_b64 s[12:13], s[6:7]
	ds_write_b32 v189, v214 offset:128
	s_or_b64 exec, exec, s[12:13]
	s_waitcnt lgkmcnt(0)
	v_add_u32_e32 v163, v181, v180
	ds_read_b128 v[164:167], v163 offset:224
	ds_read_b128 v[168:171], v163 offset:192
	ds_read_b128 v[172:175], v163 offset:160
	ds_read_b128 v[216:219], v163 offset:128
	s_waitcnt lgkmcnt(3)
	v_pk_mul_f32 v[12:13], v[12:13], v[164:165]
	s_waitcnt lgkmcnt(2)
	v_pk_mul_f32 v[8:9], v[8:9], v[168:169]
	s_waitcnt lgkmcnt(1)
	v_pk_mul_f32 v[4:5], v[4:5], v[172:173]
	v_pk_mul_f32 v[14:15], v[14:15], v[166:167]
	v_pk_mul_f32 v[10:11], v[10:11], v[170:171]
	v_pk_mul_f32 v[6:7], v[6:7], v[174:175]
	s_waitcnt lgkmcnt(0)
	v_pk_mul_f32 v[2:3], v[2:3], v[218:219]
	v_pk_mul_f32 v[0:1], v[0:1], v[216:217]
	v_pk_mul_f32 v[60:61], v[60:61], v[164:165]
	v_pk_mul_f32 v[56:57], v[56:57], v[168:169]
	v_pk_mul_f32 v[52:53], v[52:53], v[172:173]
	v_pk_mul_f32 v[62:63], v[62:63], v[166:167]
	v_pk_mul_f32 v[58:59], v[58:59], v[170:171]
	v_pk_mul_f32 v[54:55], v[54:55], v[174:175]
	v_pk_mul_f32 v[50:51], v[50:51], v[218:219]
	v_pk_mul_f32 v[48:49], v[48:49], v[216:217]
	v_pk_mul_f32 v[44:45], v[44:45], v[164:165]
	v_pk_mul_f32 v[40:41], v[40:41], v[168:169]
	v_pk_mul_f32 v[36:37], v[36:37], v[172:173]
	v_pk_mul_f32 v[46:47], v[46:47], v[166:167]
	v_pk_mul_f32 v[42:43], v[42:43], v[170:171]
	v_pk_mul_f32 v[38:39], v[38:39], v[174:175]
	v_pk_mul_f32 v[34:35], v[34:35], v[218:219]
	v_pk_mul_f32 v[32:33], v[32:33], v[216:217]
	v_pk_mul_f32 v[28:29], v[28:29], v[164:165]
	v_pk_mul_f32 v[24:25], v[24:25], v[168:169]
	v_pk_mul_f32 v[20:21], v[20:21], v[172:173]
	v_pk_mul_f32 v[30:31], v[30:31], v[166:167]
	v_pk_mul_f32 v[26:27], v[26:27], v[170:171]
	v_pk_mul_f32 v[22:23], v[22:23], v[174:175]
	v_pk_mul_f32 v[18:19], v[18:19], v[218:219]
	v_pk_mul_f32 v[16:17], v[16:17], v[216:217]
.LBB0_606:
	s_lshl_b32 s8, s65, 5
	v_add_u32_e32 v232, 0x10000, v251
	s_add_i32 m0, s8, 0xc000
	v_add_co_u32_e32 v232, vcc, v232, v182
	s_nop 1
	v_addc_co_u32_e32 v233, vcc, -1, v183, vcc
	global_load_lds_dwordx4 v[232:233], off
	v_add_u32_e32 v232, 0x10000, v255
	s_add_i32 m0, s8, 0xc400
	v_add_co_u32_e32 v232, vcc, v232, v182
	s_nop 1
	v_addc_co_u32_e32 v233, vcc, -1, v183, vcc
	global_load_lds_dwordx4 v[232:233], off
	v_mov_b32_e32 v162, v80
	v_mov_b32_e32 v163, v81
	v_mov_b32_e32 v164, v82
	v_mov_b32_e32 v175, v83
	v_mov_b32_e32 v176, v84
	v_mov_b32_e32 v177, v85
	v_mov_b32_e32 v165, v86
	v_mov_b32_e32 v174, v87
	v_mov_b32_e32 v166, v88
	v_mov_b32_e32 v167, v89
	v_mov_b32_e32 v172, v90
	v_mov_b32_e32 v173, v91
	v_mov_b32_e32 v168, v92
	v_mov_b32_e32 v169, v93
	v_mov_b32_e32 v170, v94
	v_mov_b32_e32 v171, v95
	v_fmamk_f32 v223, v64, 0x3e0293ee, v213
	v_fmamk_f32 v224, v65, 0x3e0293ee, v213
	v_fmamk_f32 v225, v66, 0x3e0293ee, v213
	v_fmamk_f32 v226, v67, 0x3e0293ee, v213
	v_fmamk_f32 v227, v68, 0x3e0293ee, v213
	v_fmamk_f32 v216, v69, 0x3e0293ee, v213
	v_fmamk_f32 v217, v70, 0x3e0293ee, v213
	v_fmamk_f32 v218, v71, 0x3e0293ee, v213
	v_fmamk_f32 v219, v72, 0x3e0293ee, v213
	v_fmamk_f32 v220, v73, 0x3e0293ee, v213
	v_fmamk_f32 v221, v74, 0x3e0293ee, v213
	v_fmamk_f32 v222, v75, 0x3e0293ee, v213
	v_fmamk_f32 v215, v76, 0x3e0293ee, v213
	v_fmamk_f32 v228, v77, 0x3e0293ee, v213
	v_fmamk_f32 v229, v78, 0x3e0293ee, v213
	v_fmac_f32_e32 v213, 0x3e0293ee, v79
	ds_read_b128 v[64:67], v192 offset:32768
	ds_read_b128 v[68:71], v192 offset:40960
	ds_read_b128 v[242:245], v201 offset:32768
	ds_read_b128 v[246:249], v201 offset:40960
	v_add_f32_e32 v230, 0, v162
	v_add_f32_e32 v230, v163, v230
	s_waitcnt lgkmcnt(3)
	v_mfma_f32_32x32x16_bf16 v[80:95], v[64:67], v[126:129], 0
	v_add_f32_e32 v230, v164, v230
	v_add_f32_e32 v230, v175, v230
	v_add_f32_e32 v230, v176, v230
	v_add_f32_e32 v230, v177, v230
	v_add_f32_e32 v230, v165, v230
	v_add_f32_e32 v230, v174, v230
	v_add_f32_e32 v230, v166, v230
	s_waitcnt lgkmcnt(2)
	v_mfma_f32_32x32x16_bf16 v[64:79], v[68:71], v[126:129], 0
	v_add_f32_e32 v230, v167, v230
	v_add_f32_e32 v230, v172, v230
	v_add_f32_e32 v230, v173, v230
	v_exp_f32_e32 v223, v223
	v_add_f32_e32 v230, v168, v230
	v_exp_f32_e32 v224, v224
	v_add_f32_e32 v230, v169, v230
	s_waitcnt lgkmcnt(1)
	v_mfma_f32_32x32x16_bf16 v[80:95], v[242:245], v[122:125], v[80:95]
	v_exp_f32_e32 v225, v225
	v_add_f32_e32 v230, v170, v230
	v_exp_f32_e32 v226, v226
	v_add_f32_e32 v230, v171, v230
	v_exp_f32_e32 v227, v227
	v_add_f32_e32 v230, v223, v230
	v_exp_f32_e32 v216, v216
	s_waitcnt lgkmcnt(0)
	v_mfma_f32_32x32x16_bf16 v[64:79], v[246:249], v[122:125], v[64:79]
	ds_read_b128 v[242:245], v200 offset:32768
	ds_read_b128 v[246:249], v200 offset:40960
	v_add_f32_e32 v230, v224, v230
	v_exp_f32_e32 v217, v217
	v_add_f32_e32 v230, v225, v230
	v_exp_f32_e32 v218, v218
	v_add_f32_e32 v230, v226, v230
	v_exp_f32_e32 v219, v219
	s_waitcnt lgkmcnt(1)
	v_mfma_f32_32x32x16_bf16 v[80:95], v[242:245], v[134:137], v[80:95]
	v_add_f32_e32 v230, v227, v230
	v_exp_f32_e32 v220, v220
	v_add_f32_e32 v230, v216, v230
	v_exp_f32_e32 v221, v221
	v_add_f32_e32 v230, v217, v230
	v_exp_f32_e32 v222, v222
	v_add_f32_e32 v230, v218, v230
	s_waitcnt lgkmcnt(0)
	v_mfma_f32_32x32x16_bf16 v[64:79], v[246:249], v[134:137], v[64:79]
	ds_read_b128 v[242:245], v195 offset:32768
	ds_read_b128 v[246:249], v195 offset:40960
	v_exp_f32_e32 v215, v215
	v_add_f32_e32 v230, v219, v230
	v_exp_f32_e32 v228, v228
	v_add_f32_e32 v230, v220, v230
	v_exp_f32_e32 v229, v229
	v_add_f32_e32 v230, v221, v230
	s_waitcnt lgkmcnt(1)
; #define SBAR() __builtin_amdgcn_sched_barrier(0)
; #define SLOAD(i, k0) do { sr_[i].vs0 = St::ld8(&Vh[(long)((k0) + sr) * LDK + sc]); sr_[i].vs1 = St::ld8(&Vh[(long)((k0) + 32 + sr) * LDK + sc]); \
;     sr_[i].ks0 = St::ld8(&Kh[(long)((k0) + sr) * LDK + sc]); sr_[i].ks1 = St::ld8(&Kh[(long)((k0) + 32 + sr) * LDK + sc]); } while (0)
; __device__ __forceinline__ void finishSM(f32x16& p0, f32x16& p1, float alpha, float& l_reg, bf16x8& pa0, bf16x8& pa1, bf16x8& pa2, bf16x8& pa3) {
;   for (int r = 0; r < 16; ++r) p1[r] = __builtin_amdgcn_exp2f(p1[r]);
;   float ps = 0; for (int r = 0; r < 16; ++r) ps += p0[r]; for (int r = 0; r < 16; ++r) ps += p1[r];
;   { auto rr = __builtin_amdgcn_permlane32_swap(__float_as_uint(ps), __float_as_uint(ps), false, false);
;     ps = __uint_as_float(rr[0]) + __uint_as_float(rr[1]); }
;   l_reg = l_reg * alpha + ps;
;     ...
;   PK4(p0, 0, pa0); PK4(p0, 8, pa1); PK4(p1, 0, pa2); PK4(p1, 8, pa3);
;     ...
; }
; __device__ __forceinline__ void qkt(f32x16& p0, f32x16& p1, const bf16* Ks, const bf16x8* qr, int r32, int hi) {
;   p0 = f32x16{}; p1 = f32x16{};
;   for (int d0 = 0; d0 < 8; ++d0) { int cb = (d0 * 16 + hi * 8) * 2;
;     bf16x8 b0 = *reinterpret_cast<const bf16x8*>((const char*)Ks + KSWZ(r32, cb));
;     bf16x8 b1 = *reinterpret_cast<const bf16x8*>((const char*)Ks + KSWZ(32 + r32, cb));
;     p0 = __builtin_amdgcn_mfma_f32_32x32x16_bf16(b0, qr[d0], p0, 0, 0, 0);
;     p1 = __builtin_amdgcn_mfma_f32_32x32x16_bf16(b1, qr[d0], p1, 0, 0, 0); }
; }
; __device__ __forceinline__ void attn_dense_body(const bf16* __restrict__ Qb, const bf16* __restrict__ Kh, const bf16* __restrict__ Vh,
;                                                 const unsigned short* __restrict__ Gb, unsigned short* __restrict__ Yb, int seq, char* lds, const int tid) {
;     ...
;     SBAR(); qkt(pA0, pA1, K_lds, qr, r32, hi);
;     finishSM(pB0, pB1, alB, l_reg, pa0, pa1, pa2, pa3); SBAR();
;     if (SDEPTH == 1 || j + 3 < NT) SLOAD(SE, (j + 1 + SDEPTH) * KVBLK); SBAR();
	v_mfma_f32_32x32x16_bf16 v[80:95], v[242:245], v[130:133], v[80:95]
	v_exp_f32_e32 v213, v213
	v_add_f32_e32 v230, v222, v230
	v_add_f32_e32 v230, v215, v230
	v_add_f32_e32 v230, v228, v230
	v_add_f32_e32 v230, v229, v230
	v_add_f32_e32 v231, v213, v230
	v_mov_b32_e32 v241, v231
	s_waitcnt lgkmcnt(0)
	v_mfma_f32_32x32x16_bf16 v[64:79], v[246:249], v[130:133], v[64:79]
	ds_read_b128 v[242:245], v194 offset:32768
	ds_read_b128 v[246:249], v194 offset:40960
	v_cvt_pk_bf16_f32 v162, v162, v163
	v_cvt_pk_bf16_f32 v163, v164, v175
	v_cvt_pk_bf16_f32 v164, v176, v177
	v_cvt_pk_bf16_f32 v165, v165, v174
	v_cvt_pk_bf16_f32 v166, v166, v167
	v_cvt_pk_bf16_f32 v167, v172, v173
	s_waitcnt lgkmcnt(1)
	v_mfma_f32_32x32x16_bf16 v[80:95], v[242:245], v[118:121], v[80:95]
	v_cvt_pk_bf16_f32 v168, v168, v169
	v_cvt_pk_bf16_f32 v169, v170, v171
	v_cvt_pk_bf16_f32 v170, v223, v224
	v_cvt_pk_bf16_f32 v171, v225, v226
	v_cvt_pk_bf16_f32 v172, v227, v216
	v_cvt_pk_bf16_f32 v173, v217, v218
	v_cvt_pk_bf16_f32 v174, v219, v220
	s_waitcnt lgkmcnt(0)
	v_mfma_f32_32x32x16_bf16 v[64:79], v[246:249], v[118:121], v[64:79]
	ds_read_b128 v[242:245], v193 offset:32768
	ds_read_b128 v[246:249], v193 offset:40960
	v_cvt_pk_bf16_f32 v175, v221, v222
	v_cvt_pk_bf16_f32 v176, v215, v228
	v_cvt_pk_bf16_f32 v177, v229, v213
	v_permlane32_swap_b32_e32 v231, v241
	v_permlane32_swap_b32_e32 v162, v164
	s_waitcnt lgkmcnt(1)
	v_mfma_f32_32x32x16_bf16 v[80:95], v[242:245], v[114:117], v[80:95]
	v_permlane32_swap_b32_e32 v163, v165
	v_permlane32_swap_b32_e32 v166, v168
	v_permlane32_swap_b32_e32 v167, v169
	v_permlane32_swap_b32_e32 v170, v172
	s_waitcnt lgkmcnt(0)
	v_mfma_f32_32x32x16_bf16 v[64:79], v[246:249], v[114:117], v[64:79]
	ds_read_b128 v[242:245], v207 offset:32768
	ds_read_b128 v[246:249], v207 offset:40960
	v_permlane32_swap_b32_e32 v171, v173
	v_permlane32_swap_b32_e32 v174, v176
	v_permlane32_swap_b32_e32 v175, v177
	s_waitcnt lgkmcnt(1)
	v_mfma_f32_32x32x16_bf16 v[80:95], v[242:245], v[110:113], v[80:95]
	s_waitcnt lgkmcnt(0)
	v_mfma_f32_32x32x16_bf16 v[64:79], v[246:249], v[110:113], v[64:79]
	ds_read_b128 v[242:245], v206 offset:32768
	ds_read_b128 v[246:249], v206 offset:40960
	s_waitcnt lgkmcnt(1)
	v_mfma_f32_32x32x16_bf16 v[80:95], v[242:245], v[106:109], v[80:95]
	s_waitcnt lgkmcnt(0)
	v_mfma_f32_32x32x16_bf16 v[64:79], v[246:249], v[106:109], v[64:79]
	s_cmp_ge_u32 s40, s41
	s_cselect_b64 s[12:13], -1, 0
	s_and_b64 vcc, exec, s[12:13]
	s_cbranch_vccnz .LBB0_608
	v_add_co_u32_e32 v98, vcc, 0xffff8000, v182
	s_nop 1
	v_addc_co_u32_e32 v99, vcc, -1, v183, vcc
	global_load_dwordx4 v[98:101], v[98:99], off
	s_nop 0
	global_load_dwordx4 v[138:141], v[182:183], off
; #define SBAR() __builtin_amdgcn_sched_barrier(0)
; __device__ __forceinline__ void partialSM(f32x16& p0, f32x16& p1, float& m_reg, float& mn, float& alpha) {
;   constexpr float C = SCALE * 1.4426950408889634f;
;   float pmax = p0[0]; for (int r = 1; r < 16; ++r) pmax = fmaxf(pmax, p0[r]); for (int r = 0; r < 16; ++r) pmax = fmaxf(pmax, p1[r]);
;   { auto rr = __builtin_amdgcn_permlane32_swap(__float_as_uint(pmax), __float_as_uint(pmax), false, false);
;     pmax = fmaxf(__uint_as_float(rr[0]), __uint_as_float(rr[1])); }
;   if (__builtin_expect(__all(pmax - m_reg <= THR / SCALE), 1)) { mn = m_reg; alpha = 1.f; }
;   else { mn = fmaxf(m_reg, pmax); alpha = __builtin_amdgcn_exp2f((m_reg - mn) * C); m_reg = mn; }
;   float mnC = -mn * C;
;   for (int r = 0; r < 16; ++r) p0[r] = fmaf(p0[r], C, mnC); for (int r = 0; r < 16; ++r) p1[r] = fmaf(p1[r], C, mnC);
;   for (int r = 0; r < 16; ++r) p0[r] = __builtin_amdgcn_exp2f(p0[r]);
; }
; template <int D0> __device__ __forceinline__ void pv_one(f32x16& od, int vb, bf16x8 pa0, bf16x8 pa1, bf16x8 pa2, bf16x8 pa3) {
;   const s16x4 l0 = tr_read<v_rd_off(D0, 0, 0)>(vb), h0 = tr_read<v_rd_off(D0, 0, 1)>(vb), l1 = tr_read<v_rd_off(D0, 1, 0)>(vb), h1 = tr_read<v_rd_off(D0, 1, 1)>(vb);
;   const s16x4 l2 = tr_read<v_rd_off(D0, 2, 0)>(vb), h2 = tr_read<v_rd_off(D0, 2, 1)>(vb), l3 = tr_read<v_rd_off(D0, 3, 0)>(vb), h3 = tr_read<v_rd_off(D0, 3, 1)>(vb);
;   asm volatile("s_waitcnt lgkmcnt(0)" ::: "memory"); SBAR();
;     ...
;   od = __builtin_amdgcn_mfma_f32_32x32x16_bf16(pa0, PK(l0, h0), od, 0, 0, 0);
;   od = __builtin_amdgcn_mfma_f32_32x32x16_bf16(pa1, PK(l1, h1), od, 0, 0, 0);
;   od = __builtin_amdgcn_mfma_f32_32x32x16_bf16(pa2, PK(l2, h2), od, 0, 0, 0);
;   od = __builtin_amdgcn_mfma_f32_32x32x16_bf16(pa3, PK(l3, h3), od, 0, 0, 0);
;     ...
; }
; __device__ __forceinline__ void pv_d0(f32x16* o, int vb, bf16x8 pa0, bf16x8 pa1, bf16x8 pa2, bf16x8 pa3) {
;   pv_one<0>(o[0], vb, pa0, pa1, pa2, pa3); pv_one<1>(o[1], vb, pa0, pa1, pa2, pa3); pv_one<2>(o[2], vb, pa0, pa1, pa2, pa3); pv_one<3>(o[3], vb, pa0, pa1, pa2, pa3);
.LBB0_608:
	ds_read_b64_tr_b16 v[216:217], v191 offset:0
	ds_read_b64_tr_b16 v[218:219], v191 offset:0x800
	ds_read_b64_tr_b16 v[220:221], v191 offset:0x1000
	ds_read_b64_tr_b16 v[222:223], v191 offset:0x1800
	ds_read_b64_tr_b16 v[224:225], v191 offset:0x2000
	ds_read_b64_tr_b16 v[226:227], v191 offset:0x2800
	ds_read_b64_tr_b16 v[242:243], v191 offset:0x3000
	ds_read_b64_tr_b16 v[244:245], v191 offset:0x3800
	s_waitcnt lgkmcnt(0)
	s_nop 0
	v_mfma_f32_32x32x16_bf16 v[0:15], v[162:165], v[216:219], v[0:15]
	ds_read_b64_tr_b16 v[216:217], v191 offset:0x200
	ds_read_b64_tr_b16 v[218:219], v191 offset:0xa00
	v_max_f32_e32 v232, v81, v81
	v_max_f32_e32 v233, v80, v80
	v_max_f32_e32 v232, v233, v232
	v_max3_f32 v232, v232, v82, v83
	v_max3_f32 v232, v232, v84, v85
	v_max3_f32 v232, v232, v86, v87
	v_mfma_f32_32x32x16_bf16 v[0:15], v[166:169], v[220:223], v[0:15]
	ds_read_b64_tr_b16 v[220:221], v191 offset:0x1200
	ds_read_b64_tr_b16 v[222:223], v191 offset:0x1a00
	v_max3_f32 v232, v232, v88, v89
	v_max3_f32 v232, v232, v90, v91
	v_max3_f32 v232, v232, v92, v93
	v_max3_f32 v232, v232, v94, v95
	v_max3_f32 v232, v232, v64, v65
	v_max3_f32 v232, v232, v66, v67
	v_mfma_f32_32x32x16_bf16 v[0:15], v[170:173], v[224:227], v[0:15]
	ds_read_b64_tr_b16 v[224:225], v191 offset:0x2200
	ds_read_b64_tr_b16 v[226:227], v191 offset:0x2a00
	v_max3_f32 v232, v232, v68, v69
	v_max3_f32 v232, v232, v70, v71
	v_max3_f32 v232, v232, v72, v73
	v_max3_f32 v232, v232, v74, v75
	v_max3_f32 v232, v232, v76, v77
	v_max3_f32 v232, v232, v78, v79
	v_mfma_f32_32x32x16_bf16 v[0:15], v[174:177], v[242:245], v[0:15]
	ds_read_b64_tr_b16 v[242:243], v191 offset:0x3200
	ds_read_b64_tr_b16 v[244:245], v191 offset:0x3a00
	v_mov_b32_e32 v233, v232
	s_nop 1
	v_permlane32_swap_b32_e32 v232, v233
	v_max_f32_e32 v233, v233, v233
	v_max_f32_e32 v232, v232, v232
	v_max_f32_e32 v232, v232, v233
	s_waitcnt lgkmcnt(0)
	v_mfma_f32_32x32x16_bf16 v[48:63], v[162:165], v[216:219], v[48:63]
	ds_read_b64_tr_b16 v[216:217], v191 offset:0x400
	ds_read_b64_tr_b16 v[218:219], v191 offset:0xc00
	v_sub_f32_e32 v233, v232, v210
	v_cmp_ge_f32_e32 vcc, s68, v233
	v_max_f32_e32 v233, v210, v210
	v_max_f32_e32 v232, v233, v232
	v_sub_f32_e32 v233, v210, v232
	v_mul_f32_e32 v233, 0x3e0293ee, v233
	v_mfma_f32_32x32x16_bf16 v[48:63], v[166:169], v[220:223], v[48:63]
	ds_read_b64_tr_b16 v[220:221], v191 offset:0x1400
	ds_read_b64_tr_b16 v[222:223], v191 offset:0x1c00
	s_cmp_eq_u64 vcc, exec
	s_cselect_b64 s[8:9], -1, 0
	v_exp_f32_e32 v233, v233
	v_mfma_f32_32x32x16_bf16 v[48:63], v[170:173], v[224:227], v[48:63]
	ds_read_b64_tr_b16 v[224:225], v191 offset:0x2400
	ds_read_b64_tr_b16 v[226:227], v191 offset:0x2c00
	v_cndmask_b32_e64 v210, v232, v210, s[8:9]
	v_mul_f32_e32 v250, 0xbe0293ee, v210
	v_fmamk_f32 v80, v80, 0x3e0293ee, v250
	v_fmamk_f32 v81, v81, 0x3e0293ee, v250
	v_fmamk_f32 v82, v82, 0x3e0293ee, v250
	v_fmamk_f32 v83, v83, 0x3e0293ee, v250
	v_mfma_f32_32x32x16_bf16 v[48:63], v[174:177], v[242:245], v[48:63]
	ds_read_b64_tr_b16 v[242:243], v191 offset:0x3400
	ds_read_b64_tr_b16 v[244:245], v191 offset:0x3c00
	v_fmamk_f32 v84, v84, 0x3e0293ee, v250
	v_fmamk_f32 v85, v85, 0x3e0293ee, v250
	v_fmamk_f32 v86, v86, 0x3e0293ee, v250
	v_fmamk_f32 v87, v87, 0x3e0293ee, v250
	v_fmamk_f32 v88, v88, 0x3e0293ee, v250
	v_fmamk_f32 v89, v89, 0x3e0293ee, v250
	s_waitcnt lgkmcnt(0)
	v_mfma_f32_32x32x16_bf16 v[32:47], v[162:165], v[216:219], v[32:47]
	ds_read_b64_tr_b16 v[216:217], v191 offset:0x600
	ds_read_b64_tr_b16 v[218:219], v191 offset:0xe00
	v_fmamk_f32 v90, v90, 0x3e0293ee, v250
	v_fmamk_f32 v91, v91, 0x3e0293ee, v250
	v_fmamk_f32 v92, v92, 0x3e0293ee, v250
	v_fmamk_f32 v93, v93, 0x3e0293ee, v250
	v_fmamk_f32 v94, v94, 0x3e0293ee, v250
	v_fmamk_f32 v95, v95, 0x3e0293ee, v250
	v_mfma_f32_32x32x16_bf16 v[32:47], v[166:169], v[220:223], v[32:47]
	ds_read_b64_tr_b16 v[220:221], v191 offset:0x1600
	ds_read_b64_tr_b16 v[222:223], v191 offset:0x1e00
	v_exp_f32_e32 v80, v80
	v_exp_f32_e32 v81, v81
	v_exp_f32_e32 v82, v82
	v_mfma_f32_32x32x16_bf16 v[32:47], v[170:173], v[224:227], v[32:47]
	ds_read_b64_tr_b16 v[224:225], v191 offset:0x2600
	ds_read_b64_tr_b16 v[226:227], v191 offset:0x2e00
	v_exp_f32_e32 v83, v83
	v_exp_f32_e32 v84, v84
	v_exp_f32_e32 v85, v85
	v_mfma_f32_32x32x16_bf16 v[32:47], v[174:177], v[242:245], v[32:47]
	ds_read_b64_tr_b16 v[242:243], v191 offset:0x3600
	ds_read_b64_tr_b16 v[244:245], v191 offset:0x3e00
	v_exp_f32_e32 v86, v86
	v_exp_f32_e32 v87, v87
	v_exp_f32_e32 v88, v88
	s_waitcnt lgkmcnt(0)
	v_mfma_f32_32x32x16_bf16 v[16:31], v[162:165], v[216:219], v[16:31]
	v_exp_f32_e32 v89, v89
	v_exp_f32_e32 v90, v90
	v_exp_f32_e32 v91, v91
	v_mfma_f32_32x32x16_bf16 v[16:31], v[166:169], v[220:223], v[16:31]
	v_exp_f32_e32 v92, v92
	v_exp_f32_e32 v93, v93
	v_mfma_f32_32x32x16_bf16 v[16:31], v[170:173], v[224:227], v[16:31]
	v_exp_f32_e32 v94, v94
	v_exp_f32_e32 v95, v95
	v_mfma_f32_32x32x16_bf16 v[16:31], v[174:177], v[242:245], v[16:31]
	s_waitcnt vmcnt(0)
	s_barrier
	s_waitcnt vmcnt(4)
	v_cndmask_b32_e64 v213, v233, 1.0, s[8:9]
	v_cmp_gt_f32_e32 vcc, 1.0, v213
	ds_write_b128 v204, v[146:149] offset:16384
	ds_write_b128 v205, v[150:153] offset:16384
	s_cbranch_vccz .LBB0_612
	s_and_saveexec_b64 s[18:19], s[6:7]
	ds_write_b32 v189, v213 offset:128
	s_or_b64 exec, exec, s[18:19]
	s_waitcnt lgkmcnt(0)
	v_add_u32_e32 v158, v181, v180
	ds_read_b128 v[146:149], v158 offset:224
	ds_read_b128 v[150:153], v158 offset:192
	ds_read_b128 v[154:157], v158 offset:160
	ds_read_b128 v[158:161], v158 offset:128
	s_waitcnt lgkmcnt(3)
	v_pk_mul_f32 v[12:13], v[12:13], v[146:147]
	s_waitcnt lgkmcnt(2)
	v_pk_mul_f32 v[8:9], v[8:9], v[150:151]
	s_waitcnt lgkmcnt(1)
	v_pk_mul_f32 v[4:5], v[4:5], v[154:155]
	v_pk_mul_f32 v[14:15], v[14:15], v[148:149]
	v_pk_mul_f32 v[10:11], v[10:11], v[152:153]
	v_pk_mul_f32 v[6:7], v[6:7], v[156:157]
	s_waitcnt lgkmcnt(0)
	v_pk_mul_f32 v[2:3], v[2:3], v[160:161]
	v_pk_mul_f32 v[0:1], v[0:1], v[158:159]
	v_pk_mul_f32 v[60:61], v[60:61], v[146:147]
	v_pk_mul_f32 v[56:57], v[56:57], v[150:151]
	v_pk_mul_f32 v[52:53], v[52:53], v[154:155]
	v_pk_mul_f32 v[62:63], v[62:63], v[148:149]
	v_pk_mul_f32 v[58:59], v[58:59], v[152:153]
	v_pk_mul_f32 v[54:55], v[54:55], v[156:157]
	v_pk_mul_f32 v[50:51], v[50:51], v[160:161]
	v_pk_mul_f32 v[48:49], v[48:49], v[158:159]
	v_pk_mul_f32 v[44:45], v[44:45], v[146:147]
	v_pk_mul_f32 v[40:41], v[40:41], v[150:151]
	v_pk_mul_f32 v[36:37], v[36:37], v[154:155]
	v_pk_mul_f32 v[46:47], v[46:47], v[148:149]
	v_pk_mul_f32 v[42:43], v[42:43], v[152:153]
	v_pk_mul_f32 v[38:39], v[38:39], v[156:157]
	v_pk_mul_f32 v[34:35], v[34:35], v[160:161]
	v_pk_mul_f32 v[32:33], v[32:33], v[158:159]
	v_pk_mul_f32 v[28:29], v[28:29], v[146:147]
	v_pk_mul_f32 v[24:25], v[24:25], v[150:151]
	v_pk_mul_f32 v[20:21], v[20:21], v[154:155]
	v_pk_mul_f32 v[30:31], v[30:31], v[148:149]
	v_pk_mul_f32 v[26:27], v[26:27], v[152:153]
	v_pk_mul_f32 v[22:23], v[22:23], v[156:157]
	v_pk_mul_f32 v[18:19], v[18:19], v[160:161]
	v_pk_mul_f32 v[16:17], v[16:17], v[158:159]
